# P10 final-norm loop: next row's loads prefetched into a second register set while the current row is reduced and stored
# speedup vs baseline: 1.0177x; 1.0043x over previous
; DI float frsq(float x) { return __builtin_amdgcn_rsqf(x); }
; DI void norm_row_bf16_to_f32(const bf16_t* xrow, const float* g, float* orow, int lane) {
;     u32x4 v[4]; float s = 0.f;
; #pragma unroll
;     for (int j = 0; j < 4; ++j) {
;         v[j] = *((const u32x4*)xrow + lane + 64 * j);
;         float f;
;         f = bflo(v[j].x); s += f * f; f = bfhi(v[j].x); s += f * f; f = bflo(v[j].y); s += f * f; f = bfhi(v[j].y); s += f * f;
;         f = bflo(v[j].z); s += f * f; f = bfhi(v[j].z); s += f * f; f = bflo(v[j].w); s += f * f; f = bfhi(v[j].w); s += f * f;
;     }
;     s = wave_sum(s);
;     const float rs = frsq(s * (1.0f / DM) + 1e-6f);
; #pragma unroll
;     for (int j = 0; j < 4; ++j) {
;         const f32x4 g0 = *((const f32x4*)g + 2 * (lane + 64 * j)), g1 = *((const f32x4*)g + 2 * (lane + 64 * j) + 1);
;         f32x4 o0, o1;
;         o0.x = bflo(v[j].x) * rs * g0.x; o0.y = bfhi(v[j].x) * rs * g0.y; o0.z = bflo(v[j].y) * rs * g0.z; o0.w = bfhi(v[j].y) * rs * g0.w;
;         o1.x = bflo(v[j].z) * rs * g1.x; o1.y = bfhi(v[j].z) * rs * g1.y; o1.z = bflo(v[j].w) * rs * g1.z; o1.w = bfhi(v[j].w) * rs * g1.w;
;         *((f32x4*)orow + 2 * (lane + 64 * j)) = o0; *((f32x4*)orow + 2 * (lane + 64 * j) + 1) = o1;
;     }
.LBB0_1160:
	s_or_b64 exec, exec, s[2:3]
	s_waitcnt lgkmcnt(0)
	s_barrier
	v_readlane_b32 s2, v234, 10
	v_readfirstlane_b32 s0, v167
	s_ashr_i32 s0, s0, 6
	s_add_i32 s4, s0, s2
	s_cmpk_gt_i32 s4, 0x7fff
	s_cbranch_scc1 .LBB0_1163
	v_mbcnt_hi_u32_b32 v0, -1, v169
	v_and_b32_e32 v1, 64, v0
	v_add_u32_e32 v1, 64, v1
	v_xor_b32_e32 v2, 1, v0
	v_cmp_lt_i32_e32 vcc, v2, v1
	s_ashr_i32 s1, s0, 31
	s_ashr_i32 s3, s2, 31
	v_cndmask_b32_e32 v2, v0, v2, vcc
	v_lshlrev_b32_e32 v10, 2, v2
	v_xor_b32_e32 v2, 2, v0
	v_cmp_lt_i32_e32 vcc, v2, v1
	s_add_u32 s2, s0, s2
	s_addc_u32 s3, s1, s3
	v_cndmask_b32_e32 v2, v0, v2, vcc
	v_lshlrev_b32_e32 v11, 2, v2
	v_xor_b32_e32 v2, 4, v0
	v_cmp_lt_i32_e32 vcc, v2, v1
	s_lshl_b64 s[0:1], s[2:3], 13
	v_and_b32_e32 v16, 63, v167
	v_cndmask_b32_e32 v2, v0, v2, vcc
	v_lshlrev_b32_e32 v12, 2, v2
	v_xor_b32_e32 v2, 8, v0
	v_cmp_lt_i32_e32 vcc, v2, v1
	s_add_u32 s0, s60, s0
	v_lshlrev_b32_e32 v8, 5, v16
	v_cndmask_b32_e32 v2, v0, v2, vcc
	v_lshlrev_b32_e32 v13, 2, v2
	v_xor_b32_e32 v2, 16, v0
	v_cmp_lt_i32_e32 vcc, v2, v1
	v_mov_b32_e32 v9, 0
	s_addc_u32 s1, s61, s1
	v_cndmask_b32_e32 v2, v0, v2, vcc
	v_lshlrev_b32_e32 v14, 2, v2
	v_xor_b32_e32 v2, 32, v0
	v_readlane_b32 s8, v234, 0
	v_lshl_add_u64 v[6:7], s[0:1], 0, v[8:9]
	s_mov_b64 s[0:1], 0x1000
	s_ashr_i32 s59, s58, 31
	v_cmp_lt_i32_e32 vcc, v2, v1
	v_readlane_b32 s14, v234, 6
	v_readlane_b32 s15, v234, 7
	v_lshl_add_u64 v[6:7], v[6:7], 0, s[0:1]
	s_lshl_b64 s[0:1], s[58:59], 13
	s_lshl_b64 s[2:3], s[2:3], 12
	v_cndmask_b32_e32 v0, v0, v2, vcc
	s_mov_b64 s[6:7], s[14:15]
	s_add_u32 s2, s62, s2
	v_lshlrev_b32_e32 v15, 2, v0
	v_lshl_add_u64 v[0:1], s[6:7], 0, v[8:9]
	v_or_b32_e32 v2, 0x1000, v8
	v_or_b32_e32 v4, 0x1800, v8
	v_lshlrev_b32_e32 v8, 4, v16
	s_addc_u32 s3, s63, s3
	v_mov_b32_e32 v3, v9
	v_mov_b32_e32 v5, v9
	v_lshl_add_u64 v[8:9], s[2:3], 0, v[8:9]
	s_mov_b64 s[2:3], 0xc00
	v_lshl_add_u64 v[2:3], s[6:7], 0, v[2:3]
	v_lshl_add_u64 v[4:5], s[6:7], 0, v[4:5]
	v_lshl_add_u64 v[8:9], v[8:9], 0, s[2:3]
	s_lshl_b64 s[2:3], s[58:59], 12
	v_mov_b32_e32 v16, 0x358637bd
	v_readlane_b32 s9, v234, 1
	v_readlane_b32 s10, v234, 2
	v_readlane_b32 s11, v234, 3
	v_readlane_b32 s12, v234, 4
	v_readlane_b32 s13, v234, 5
	global_load_dwordx4 v[96:99], v[0:1], off
	global_load_dwordx4 v[100:103], v[0:1], off offset:16
	global_load_dwordx4 v[104:107], v[0:1], off offset:2048
	global_load_dwordx4 v[108:111], v[0:1], off offset:2064
	global_load_dwordx4 v[112:115], v[2:3], off
	global_load_dwordx4 v[116:119], v[2:3], off offset:16
	global_load_dwordx4 v[120:123], v[4:5], off
	global_load_dwordx4 v[124:127], v[4:5], off offset:16
	global_load_dwordx4 v[128:131], v[8:9], off
	global_load_dwordx4 v[132:135], v[8:9], off offset:-3072
	global_load_dwordx4 v[136:139], v[8:9], off offset:-2048
	global_load_dwordx4 v[140:143], v[8:9], off offset:-1024
	v_lshl_add_u64 v[8:9], v[8:9], 0, s[2:3]
	s_waitcnt vmcnt(0)
.LBB0_1162:
	s_waitcnt vmcnt(8)
	v_mov_b32_e32 v18, v128
	v_mov_b32_e32 v19, v129
	v_mov_b32_e32 v20, v130
	v_mov_b32_e32 v21, v131
	v_mov_b32_e32 v22, v132
	v_mov_b32_e32 v23, v133
	v_mov_b32_e32 v24, v134
	v_mov_b32_e32 v25, v135
	v_mov_b32_e32 v26, v136
	v_mov_b32_e32 v27, v137
	v_mov_b32_e32 v28, v138
	v_mov_b32_e32 v29, v139
	v_mov_b32_e32 v30, v140
	v_mov_b32_e32 v31, v141
	v_mov_b32_e32 v32, v142
	v_mov_b32_e32 v33, v143
	s_add_i32 s4, s4, s58
	s_cmpk_gt_i32 s4, 0x7fff
	s_cbranch_scc1 .Lp10_nopf
	global_load_dwordx4 v[128:131], v[8:9], off
	global_load_dwordx4 v[132:135], v[8:9], off offset:-3072
	global_load_dwordx4 v[136:139], v[8:9], off offset:-2048
	global_load_dwordx4 v[140:143], v[8:9], off offset:-1024
	v_lshl_add_u64 v[8:9], v[8:9], 0, s[2:3]
; DI float frsq(float x) { return __builtin_amdgcn_rsqf(x); }
; DI void norm_row_bf16_to_f32(const bf16_t* xrow, const float* g, float* orow, int lane) {
;     u32x4 v[4]; float s = 0.f;
; #pragma unroll
;     for (int j = 0; j < 4; ++j) {
;         v[j] = *((const u32x4*)xrow + lane + 64 * j);
;         float f;
;         f = bflo(v[j].x); s += f * f; f = bfhi(v[j].x); s += f * f; f = bflo(v[j].y); s += f * f; f = bfhi(v[j].y); s += f * f;
;         f = bflo(v[j].z); s += f * f; f = bfhi(v[j].z); s += f * f; f = bflo(v[j].w); s += f * f; f = bfhi(v[j].w); s += f * f;
;     }
;     s = wave_sum(s);
;     const float rs = frsq(s * (1.0f / DM) + 1e-6f);
; #pragma unroll
;     for (int j = 0; j < 4; ++j) {
;         const f32x4 g0 = *((const f32x4*)g + 2 * (lane + 64 * j)), g1 = *((const f32x4*)g + 2 * (lane + 64 * j) + 1);
;         f32x4 o0, o1;
;         o0.x = bflo(v[j].x) * rs * g0.x; o0.y = bfhi(v[j].x) * rs * g0.y; o0.z = bflo(v[j].y) * rs * g0.z; o0.w = bfhi(v[j].y) * rs * g0.w;
;         o1.x = bflo(v[j].z) * rs * g1.x; o1.y = bfhi(v[j].z) * rs * g1.y; o1.z = bflo(v[j].w) * rs * g1.z; o1.w = bfhi(v[j].w) * rs * g1.w;
;         *((f32x4*)orow + 2 * (lane + 64 * j)) = o0; *((f32x4*)orow + 2 * (lane + 64 * j) + 1) = o1;
;     }
.Lp10_nopf:
	v_and_b32_e32 v42, 0xffff0000, v21
	v_lshlrev_b32_e32 v46, 16, v22
	v_and_b32_e32 v47, 0xffff0000, v22
	v_lshlrev_b32_e32 v22, 16, v23
	v_and_b32_e32 v23, 0xffff0000, v23
	v_pk_mul_f32 v[64:65], v[46:47], v[46:47]
	v_pk_mul_f32 v[66:67], v[22:23], v[22:23]
	v_add_f32_e32 v17, v65, v64
	v_lshlrev_b32_e32 v44, 16, v24
	v_and_b32_e32 v45, 0xffff0000, v24
	v_add_f32_e32 v17, v66, v17
	v_lshlrev_b32_e32 v43, 16, v21
	v_lshlrev_b32_e32 v56, 16, v20
	v_and_b32_e32 v57, 0xffff0000, v20
	v_pk_mul_f32 v[20:21], v[44:45], v[44:45]
	v_add_f32_e32 v17, v67, v17
	v_lshlrev_b32_e32 v24, 16, v25
	v_and_b32_e32 v25, 0xffff0000, v25
	v_add_f32_e32 v17, v20, v17
	v_pk_mul_f32 v[62:63], v[24:25], v[24:25]
	v_add_f32_e32 v17, v21, v17
	v_lshlrev_b32_e32 v50, 16, v26
	v_and_b32_e32 v51, 0xffff0000, v26
	v_add_f32_e32 v17, v62, v17
	v_pk_mul_f32 v[72:73], v[50:51], v[50:51]
	v_add_f32_e32 v17, v63, v17
	v_lshlrev_b32_e32 v26, 16, v27
	v_and_b32_e32 v27, 0xffff0000, v27
	v_add_f32_e32 v17, v72, v17
	v_pk_mul_f32 v[74:75], v[26:27], v[26:27]
	v_add_f32_e32 v17, v73, v17
	v_lshlrev_b32_e32 v48, 16, v28
	v_and_b32_e32 v49, 0xffff0000, v28
	v_add_f32_e32 v17, v74, v17
	v_pk_mul_f32 v[68:69], v[48:49], v[48:49]
	v_add_f32_e32 v17, v75, v17
	v_lshlrev_b32_e32 v28, 16, v29
	v_and_b32_e32 v29, 0xffff0000, v29
	v_add_f32_e32 v17, v68, v17
	v_pk_mul_f32 v[70:71], v[28:29], v[28:29]
	v_add_f32_e32 v17, v69, v17
	v_lshlrev_b32_e32 v54, 16, v30
	v_and_b32_e32 v55, 0xffff0000, v30
	v_add_f32_e32 v17, v70, v17
	v_pk_mul_f32 v[80:81], v[54:55], v[54:55]
	v_add_f32_e32 v17, v71, v17
	v_lshlrev_b32_e32 v30, 16, v31
	v_and_b32_e32 v31, 0xffff0000, v31
	v_add_f32_e32 v17, v80, v17
	v_pk_mul_f32 v[82:83], v[30:31], v[30:31]
	v_add_f32_e32 v17, v81, v17
	v_lshlrev_b32_e32 v52, 16, v32
	v_and_b32_e32 v53, 0xffff0000, v32
	v_add_f32_e32 v17, v82, v17
	v_pk_mul_f32 v[76:77], v[52:53], v[52:53]
	v_add_f32_e32 v17, v83, v17
	v_lshlrev_b32_e32 v32, 16, v33
	v_and_b32_e32 v33, 0xffff0000, v33
	v_add_f32_e32 v17, v76, v17
	v_pk_mul_f32 v[78:79], v[32:33], v[32:33]
	v_add_f32_e32 v17, v77, v17
	v_lshlrev_b32_e32 v58, 16, v18
	v_and_b32_e32 v59, 0xffff0000, v18
	v_add_f32_e32 v17, v78, v17
	v_pk_mul_f32 v[86:87], v[58:59], v[58:59]
	v_add_f32_e32 v17, v79, v17
	v_lshlrev_b32_e32 v60, 16, v19
	v_and_b32_e32 v61, 0xffff0000, v19
	v_add_f32_e32 v17, v86, v17
	v_pk_mul_f32 v[88:89], v[60:61], v[60:61]
	v_add_f32_e32 v17, v87, v17
	v_add_f32_e32 v17, v88, v17
	v_pk_mul_f32 v[84:85], v[56:57], v[56:57]
	v_add_f32_e32 v17, v89, v17
	v_add_f32_e32 v17, v84, v17
	v_pk_mul_f32 v[18:19], v[42:43], v[42:43]
	v_add_f32_e32 v17, v85, v17
	v_add_f32_e32 v17, v19, v17
	v_add_f32_e32 v17, v18, v17
	ds_bpermute_b32 v18, v10, v17
	s_waitcnt lgkmcnt(0)
	v_add_f32_e32 v17, v17, v18
	ds_bpermute_b32 v18, v11, v17
	s_waitcnt lgkmcnt(0)
	v_add_f32_e32 v17, v17, v18
	ds_bpermute_b32 v18, v12, v17
	s_waitcnt lgkmcnt(0)
	v_add_f32_e32 v17, v17, v18
	ds_bpermute_b32 v18, v13, v17
	s_waitcnt lgkmcnt(0)
	v_add_f32_e32 v17, v17, v18
	ds_bpermute_b32 v18, v14, v17
	s_waitcnt lgkmcnt(0)
	v_add_f32_e32 v17, v17, v18
	ds_bpermute_b32 v18, v15, v17
	s_waitcnt lgkmcnt(0)
	v_add_f32_e32 v17, v17, v18
	v_fmamk_f32 v17, v17, 0x3a000000, v16
	v_rsq_f32_e32 v62, v17
	s_nop 0
	v_pk_mul_f32 v[18:19], v[62:63], v[46:47] op_sel_hi:[0,1]
	v_pk_mul_f32 v[20:21], v[62:63], v[22:23] op_sel_hi:[0,1]
	v_pk_mul_f32 v[22:23], v[62:63], v[44:45] op_sel_hi:[0,1]
	v_pk_mul_f32 v[24:25], v[62:63], v[24:25] op_sel_hi:[0,1]
	v_pk_mul_f32 v[20:21], v[98:99], v[20:21]
	v_pk_mul_f32 v[18:19], v[96:97], v[18:19]
	v_pk_mul_f32 v[24:25], v[102:103], v[24:25]
	v_pk_mul_f32 v[22:23], v[100:101], v[22:23]
	global_store_dwordx4 v[6:7], v[18:21], off offset:-4096
	global_store_dwordx4 v[6:7], v[22:25], off offset:-4080
	v_pk_mul_f32 v[26:27], v[62:63], v[26:27] op_sel_hi:[0,1]
	v_pk_mul_f32 v[34:35], v[62:63], v[50:51] op_sel_hi:[0,1]
	v_pk_mul_f32 v[28:29], v[62:63], v[28:29] op_sel_hi:[0,1]
	v_pk_mul_f32 v[36:37], v[62:63], v[48:49] op_sel_hi:[0,1]
	v_pk_mul_f32 v[18:19], v[104:105], v[34:35]
	v_pk_mul_f32 v[20:21], v[106:107], v[26:27]
	v_pk_mul_f32 v[22:23], v[108:109], v[36:37]
	v_pk_mul_f32 v[24:25], v[110:111], v[28:29]
	global_store_dwordx4 v[6:7], v[18:21], off offset:-2048
	global_store_dwordx4 v[6:7], v[22:25], off offset:-2032
	v_pk_mul_f32 v[26:27], v[62:63], v[30:31] op_sel_hi:[0,1]
	v_pk_mul_f32 v[28:29], v[62:63], v[54:55] op_sel_hi:[0,1]
	v_pk_mul_f32 v[30:31], v[62:63], v[32:33] op_sel_hi:[0,1]
	v_pk_mul_f32 v[32:33], v[62:63], v[52:53] op_sel_hi:[0,1]
	v_pk_mul_f32 v[18:19], v[112:113], v[28:29]
	v_pk_mul_f32 v[20:21], v[114:115], v[26:27]
	v_pk_mul_f32 v[22:23], v[116:117], v[32:33]
	v_pk_mul_f32 v[24:25], v[118:119], v[30:31]
	global_store_dwordx4 v[6:7], v[18:21], off
	global_store_dwordx4 v[6:7], v[22:25], off offset:16
	v_pk_mul_f32 v[26:27], v[62:63], v[60:61] op_sel_hi:[0,1]
	v_pk_mul_f32 v[28:29], v[62:63], v[58:59] op_sel_hi:[0,1]
	v_pk_mul_f32 v[30:31], v[62:63], v[56:57] op_sel_hi:[0,1]
	v_pk_mul_f32 v[32:33], v[62:63], v[42:43] op_sel_hi:[0,1]
	v_pk_mul_f32 v[18:19], v[120:121], v[28:29]
	v_pk_mul_f32 v[20:21], v[122:123], v[26:27]
	v_pk_mul_f32 v[22:23], v[124:125], v[30:31]
	v_pk_mul_f32 v[24:25], v[126:127], v[32:33] op_sel:[0,1] op_sel_hi:[1,0]
	global_store_dwordx4 v[6:7], v[18:21], off offset:2048
	global_store_dwordx4 v[6:7], v[22:25], off offset:2064
	v_lshl_add_u64 v[6:7], v[6:7], 0, s[0:1]
	s_cbranch_scc0 .LBB0_1162
